# v31 + unnecessary vmcnt(0) removed at ctx scan MFMA half-step
# speedup vs baseline: 1.0374x; 1.0075x over previous
.LBB0_1037:
	s_lshl_b32 s6, s6, 10
	s_lshl_b64 s[14:15], s[6:7], 2
	s_add_u32 s2, s56, s14
	s_addc_u32 s6, s57, s15
	s_lshl_b32 s14, s43, 2
	s_add_u32 s2, s2, s14
	s_addc_u32 s6, s6, 0
	s_add_u32 s14, s2, s85
	s_addc_u32 s15, s6, 0
	v_lshl_add_u64 v[130:131], s[14:15], 0, v[154:155]
	v_add_co_u32_e32 v132, vcc, s86, v130
	s_mov_b64 s[14:15], 0x4f000
	s_nop 0
	v_addc_co_u32_e32 v133, vcc, 0, v131, vcc
	global_load_dwordx4 v[142:145], v[132:133], off
	v_lshl_add_u64 v[130:131], v[130:131], 0, s[14:15]
	global_load_dwordx4 v[138:141], v[130:131], off offset:16
	global_load_dwordx4 v[134:137], v[130:131], off offset:512
	s_nop 0
	global_load_dwordx4 v[130:133], v[130:131], off offset:528
	v_mov_b32_e32 v164, v1
	v_mov_b32_e32 v165, v170
	v_mul_f32_e32 v127, 0xbfb8aa3b, v127
	v_lshl_add_u32 v166, v165, 3, s78
	v_add_u32_e32 v164, s77, v164
	v_ashrrev_i32_e32 v165, 31, v164
	v_lshlrev_b64 v[168:169], 11, v[164:165]
	v_exp_f32_e32 v127, v127
	v_mul_f32_e32 v126, 0xbfb8aa3b, v126
	v_exp_f32_e32 v182, v126
	v_mul_f32_e32 v122, 0xbfb8aa3b, v122
	v_add_f32_e32 v127, 1.0, v127
	v_rcp_f32_e32 v127, v127
	v_mul_f32_e32 v123, 0xbfb8aa3b, v123
	v_mul_f32_e32 v124, 0xbfb8aa3b, v124
	v_mul_f32_e32 v125, 0xbfb8aa3b, v125
	v_exp_f32_e32 v122, v122
	v_exp_f32_e32 v123, v123
	v_exp_f32_e32 v124, v124
	v_exp_f32_e32 v125, v125
	v_add_f32_e32 v122, 1.0, v122
	v_add_f32_e32 v123, 1.0, v123
	v_add_f32_e32 v124, 1.0, v124
	v_add_f32_e32 v125, 1.0, v125
	v_rcp_f32_e32 v122, v122
	v_rcp_f32_e32 v123, v123
	v_rcp_f32_e32 v124, v124
	v_rcp_f32_e32 v125, v125
	v_mul_f32_e32 v118, 0xbfb8aa3b, v118
	v_mul_f32_e32 v114, 0xbfb8aa3b, v114
	v_exp_f32_e32 v114, v114
	v_mul_f32_e32 v119, 0xbfb8aa3b, v119
	v_exp_f32_e32 v119, v119
	v_mul_f32_e32 v120, 0xbfb8aa3b, v120
	v_add_f32_e32 v114, 1.0, v114
	v_rcp_f32_e32 v114, v114
	v_exp_f32_e32 v120, v120
	v_mul_f32_e32 v121, 0xbfb8aa3b, v121
	v_exp_f32_e32 v121, v121
	v_mul_f32_e32 v110, 0xbfb8aa3b, v110
	v_mul_f32_e32 v111, 0xbfb8aa3b, v111
	v_exp_f32_e32 v110, v110
	v_mul_f32_e32 v106, 0xbfb8aa3b, v106
	v_exp_f32_e32 v111, v111
	v_mul_f32_e32 v107, 0xbfb8aa3b, v107
	v_mul_f32_e32 v112, 0xbfb8aa3b, v112
	v_mul_f32_e32 v108, 0xbfb8aa3b, v108
	v_mul_f32_e32 v113, 0xbfb8aa3b, v113
	v_mul_f32_e32 v109, 0xbfb8aa3b, v109
	v_exp_f32_e32 v106, v106
	v_exp_f32_e32 v107, v107
	v_exp_f32_e32 v112, v112
	v_exp_f32_e32 v108, v108
	v_exp_f32_e32 v113, v113
	v_exp_f32_e32 v109, v109
	v_add_f32_e32 v110, 1.0, v110
	v_add_f32_e32 v111, 1.0, v111
	v_rcp_f32_e32 v110, v110
	v_add_f32_e32 v106, 1.0, v106
	v_rcp_f32_e32 v111, v111
	v_add_f32_e32 v107, 1.0, v107
	v_add_f32_e32 v112, 1.0, v112
	v_add_f32_e32 v108, 1.0, v108
	v_add_f32_e32 v113, 1.0, v113
	v_add_f32_e32 v109, 1.0, v109
	v_mul_f32_e32 v102, 0xbfb8aa3b, v102
	v_mul_f32_e32 v98, 0xbfb8aa3b, v98
	v_mul_f32_e32 v103, 0xbfb8aa3b, v103
	v_mul_f32_e32 v99, 0xbfb8aa3b, v99
	v_mul_f32_e32 v104, 0xbfb8aa3b, v104
	v_mul_f32_e32 v100, 0xbfb8aa3b, v100
	s_waitcnt vmcnt(0)
	v_mov_b32_e32 v176, v142
	v_mul_f32_e32 v105, 0xbfb8aa3b, v105
	v_mul_f32_e32 v101, 0xbfb8aa3b, v101
	v_mov_b32_e32 v177, v143
	v_rcp_f32_e32 v106, v106
	v_rcp_f32_e32 v107, v107
	v_mov_b32_e32 v178, v142
	v_rcp_f32_e32 v112, v112
	v_rcp_f32_e32 v108, v108
	v_rcp_f32_e32 v113, v113
	v_rcp_f32_e32 v109, v109
	v_exp_f32_e32 v102, v102
	v_exp_f32_e32 v98, v98
	v_mov_b32_e32 v178, v144
	v_exp_f32_e32 v103, v103
	v_exp_f32_e32 v99, v99
	v_exp_f32_e32 v104, v104
	v_exp_f32_e32 v100, v100
	v_exp_f32_e32 v105, v105
	v_exp_f32_e32 v101, v101
	v_mul_f32_e32 v94, 0xbfb8aa3b, v94
	v_mul_f32_e32 v95, 0xbfb8aa3b, v95
	v_add_f32_e32 v102, 1.0, v102
	v_add_f32_e32 v98, 1.0, v98
	v_add_f32_e32 v103, 1.0, v103
	v_add_f32_e32 v99, 1.0, v99
	v_add_f32_e32 v104, 1.0, v104
	v_add_f32_e32 v100, 1.0, v100
	v_add_f32_e32 v105, 1.0, v105
	v_add_f32_e32 v101, 1.0, v101
	v_exp_f32_e32 v94, v94
	v_mul_f32_e32 v90, 0xbfb8aa3b, v90
	v_exp_f32_e32 v95, v95
	v_mul_f32_e32 v91, 0xbfb8aa3b, v91
	v_mul_f32_e32 v96, 0xbfb8aa3b, v96
	v_mul_f32_e32 v92, 0xbfb8aa3b, v92
	v_mul_f32_e32 v97, 0xbfb8aa3b, v97
	v_mul_f32_e32 v93, 0xbfb8aa3b, v93
	v_rcp_f32_e32 v102, v102
	v_rcp_f32_e32 v98, v98
	v_rcp_f32_e32 v103, v103
	v_rcp_f32_e32 v99, v99
	v_rcp_f32_e32 v104, v104
	v_rcp_f32_e32 v100, v100
	v_rcp_f32_e32 v105, v105
	v_rcp_f32_e32 v101, v101
	v_exp_f32_e32 v90, v90
	v_exp_f32_e32 v91, v91
	v_exp_f32_e32 v96, v96
	v_exp_f32_e32 v92, v92
	v_exp_f32_e32 v97, v97
	v_exp_f32_e32 v93, v93
	v_add_f32_e32 v94, 1.0, v94
	v_add_f32_e32 v95, 1.0, v95
	v_rcp_f32_e32 v94, v94
	v_add_f32_e32 v90, 1.0, v90
	v_rcp_f32_e32 v95, v95
	v_add_f32_e32 v91, 1.0, v91
	v_add_f32_e32 v96, 1.0, v96
	v_add_f32_e32 v92, 1.0, v92
	v_add_f32_e32 v97, 1.0, v97
	v_add_f32_e32 v93, 1.0, v93
	v_mul_f32_e32 v86, 0xbfb8aa3b, v86
	v_mul_f32_e32 v82, 0xbfb8aa3b, v82
	v_mul_f32_e32 v87, 0xbfb8aa3b, v87
	v_mul_f32_e32 v83, 0xbfb8aa3b, v83
	v_mul_f32_e32 v88, 0xbfb8aa3b, v88
	v_mul_f32_e32 v84, 0xbfb8aa3b, v84
	v_mul_f32_e32 v89, 0xbfb8aa3b, v89
	v_mul_f32_e32 v85, 0xbfb8aa3b, v85
	v_rcp_f32_e32 v90, v90
	v_rcp_f32_e32 v91, v91
	v_mov_b32_e32 v179, v177
	v_rcp_f32_e32 v96, v96
	v_rcp_f32_e32 v92, v92
	v_mov_b32_e32 v177, v176
	v_rcp_f32_e32 v97, v97
	v_rcp_f32_e32 v93, v93
	v_mov_b32_e32 v165, v179
	v_exp_f32_e32 v86, v86
	v_exp_f32_e32 v82, v82
	v_mov_b32_e32 v176, v178
	v_exp_f32_e32 v87, v87
	v_exp_f32_e32 v83, v83
	v_exp_f32_e32 v88, v88
	v_exp_f32_e32 v84, v84
	v_exp_f32_e32 v89, v89
	v_exp_f32_e32 v85, v85
	v_mul_f32_e32 v78, 0xbfb8aa3b, v78
	v_mul_f32_e32 v79, 0xbfb8aa3b, v79
	v_add_f32_e32 v86, 1.0, v86
	v_add_f32_e32 v82, 1.0, v82
	v_add_f32_e32 v87, 1.0, v87
	v_add_f32_e32 v83, 1.0, v83
	v_add_f32_e32 v88, 1.0, v88
	v_add_f32_e32 v84, 1.0, v84
	v_mov_b32_e32 v175, v176
	v_sub_f32_e32 v185, 1.0, v175
	v_fma_f32 v112, v112, v185, v175
	v_mov_b32_e32 v178, v142
	v_log_f32_e32 v112, v112
	v_fma_f32 v96, v96, v185, v175
	v_cvt_f16_f32_e32 v112, v112
	v_add_f32_e32 v89, 1.0, v89
	v_mov_b32_e32 v178, v145
	v_add_f32_e32 v85, 1.0, v85
	v_exp_f32_e32 v78, v78
	v_mul_f32_e32 v74, 0xbfb8aa3b, v74
	v_exp_f32_e32 v79, v79
	v_mul_f32_e32 v75, 0xbfb8aa3b, v75
	v_mul_f32_e32 v80, 0xbfb8aa3b, v80
	v_mul_f32_e32 v76, 0xbfb8aa3b, v76
	v_mul_f32_e32 v81, 0xbfb8aa3b, v81
	v_mul_f32_e32 v77, 0xbfb8aa3b, v77
	v_log_f32_e32 v96, v96
	v_rcp_f32_e32 v86, v86
	v_rcp_f32_e32 v82, v82
	v_rcp_f32_e32 v87, v87
	v_rcp_f32_e32 v83, v83
	v_rcp_f32_e32 v88, v88
	v_rcp_f32_e32 v84, v84
	v_rcp_f32_e32 v89, v89
	v_rcp_f32_e32 v85, v85
	v_exp_f32_e32 v74, v74
	v_exp_f32_e32 v75, v75
	v_exp_f32_e32 v80, v80
	v_exp_f32_e32 v76, v76
	v_exp_f32_e32 v81, v81
	v_exp_f32_e32 v77, v77
	v_mov_b32_e32 v176, v178
	v_add_f32_e32 v78, 1.0, v78
	v_add_f32_e32 v79, 1.0, v79
	v_mov_b32_e32 v179, v142
	v_cvt_f16_f32_e32 v96, v96
	v_rcp_f32_e32 v78, v78
	v_add_f32_e32 v74, 1.0, v74
	v_rcp_f32_e32 v79, v79
	v_add_f32_e32 v75, 1.0, v75
	v_add_f32_e32 v80, 1.0, v80
	v_mov_b32_e32 v179, v138
	v_add_f32_e32 v76, 1.0, v76
	v_add_f32_e32 v81, 1.0, v81
	v_add_f32_e32 v77, 1.0, v77
	v_mul_f32_e32 v70, 0xbfb8aa3b, v70
	v_mul_f32_e32 v66, 0xbfb8aa3b, v66
	v_mul_f32_e32 v71, 0xbfb8aa3b, v71
	v_mul_f32_e32 v67, 0xbfb8aa3b, v67
	v_mul_f32_e32 v72, 0xbfb8aa3b, v72
	v_mul_f32_e32 v68, 0xbfb8aa3b, v68
	v_mul_f32_e32 v73, 0xbfb8aa3b, v73
	v_mul_f32_e32 v69, 0xbfb8aa3b, v69
	v_rcp_f32_e32 v74, v74
	v_rcp_f32_e32 v75, v75
	v_rcp_f32_e32 v80, v80
	v_rcp_f32_e32 v76, v76
	v_rcp_f32_e32 v81, v81
	v_rcp_f32_e32 v77, v77
	v_exp_f32_e32 v70, v70
	v_exp_f32_e32 v66, v66
	v_exp_f32_e32 v71, v71
	v_exp_f32_e32 v67, v67
	v_exp_f32_e32 v72, v72
	v_mov_b32_e32 v178, v179
	v_sub_f32_e32 v184, 1.0, v178
	v_fma_f32 v122, v122, v184, v178
	v_mov_b32_e32 v180, v142
	v_log_f32_e32 v122, v122
	v_fma_f32 v106, v106, v184, v178
	v_cvt_f16_f32_e32 v122, v122
	v_log_f32_e32 v106, v106
	v_fma_f32 v90, v90, v184, v178
	v_log_f32_e32 v90, v90
	v_exp_f32_e32 v68, v68
	v_exp_f32_e32 v73, v73
	v_mov_b32_e32 v180, v139
	v_exp_f32_e32 v69, v69
	v_mul_f32_e32 v62, 0xbfb8aa3b, v62
	v_mul_f32_e32 v63, 0xbfb8aa3b, v63
	v_fma_f32 v74, v74, v184, v178
	v_fma_f32 v80, v80, v185, v175
	v_add_f32_e32 v70, 1.0, v70
	v_add_f32_e32 v66, 1.0, v66
	v_add_f32_e32 v71, 1.0, v71
	v_add_f32_e32 v67, 1.0, v67
	v_add_f32_e32 v72, 1.0, v72
	v_add_f32_e32 v68, 1.0, v68
	v_add_f32_e32 v73, 1.0, v73
	v_add_f32_e32 v69, 1.0, v69
	v_exp_f32_e32 v62, v62
	v_mul_f32_e32 v58, 0xbfb8aa3b, v58
	v_exp_f32_e32 v63, v63
	v_mul_f32_e32 v59, 0xbfb8aa3b, v59
	v_mul_f32_e32 v64, 0xbfb8aa3b, v64
	v_mul_f32_e32 v60, 0xbfb8aa3b, v60
	v_mul_f32_e32 v65, 0xbfb8aa3b, v65
	v_mov_b32_e32 v179, v180
	v_sub_f32_e32 v183, 1.0, v179
	v_mov_b32_e32 v181, v142
	v_fma_f32 v123, v123, v183, v179
	v_log_f32_e32 v123, v123
	v_fma_f32 v107, v107, v183, v179
	v_cvt_f16_f32_sdwa v123, v123 dst_sel:WORD_1 dst_unused:UNUSED_PAD src0_sel:DWORD
	v_log_f32_e32 v107, v107
	v_fma_f32 v91, v91, v183, v179
	v_log_f32_e32 v91, v91
	v_fma_f32 v75, v75, v183, v179
	v_mul_f32_e32 v61, 0xbfb8aa3b, v61
	v_log_f32_e32 v74, v74
	v_mov_b32_e32 v181, v140
	v_log_f32_e32 v75, v75
	v_log_f32_e32 v80, v80
	v_rcp_f32_e32 v70, v70
	v_rcp_f32_e32 v66, v66
	v_rcp_f32_e32 v71, v71
	v_rcp_f32_e32 v67, v67
	v_rcp_f32_e32 v72, v72
	v_rcp_f32_e32 v68, v68
	v_rcp_f32_e32 v73, v73
	v_rcp_f32_e32 v69, v69
	v_exp_f32_e32 v58, v58
	v_exp_f32_e32 v59, v59
	v_exp_f32_e32 v64, v64
	v_exp_f32_e32 v60, v60
	v_exp_f32_e32 v65, v65
	v_exp_f32_e32 v61, v61
	v_add_f32_e32 v62, 1.0, v62
	v_add_f32_e32 v63, 1.0, v63
	v_mov_b32_e32 v180, v181
	v_cvt_f16_f32_e32 v80, v80
	v_rcp_f32_e32 v62, v62
	v_mov_b32_e32 v181, v142
	v_add_f32_e32 v58, 1.0, v58
	v_rcp_f32_e32 v63, v63
	v_add_f32_e32 v59, 1.0, v59
	v_add_f32_e32 v64, 1.0, v64
	v_add_f32_e32 v60, 1.0, v60
	v_add_f32_e32 v65, 1.0, v65
	v_add_f32_e32 v61, 1.0, v61
	v_mul_f32_e32 v54, 0xbfb8aa3b, v54
	v_mul_f32_e32 v50, 0xbfb8aa3b, v50
	v_mul_f32_e32 v55, 0xbfb8aa3b, v55
	v_mul_f32_e32 v51, 0xbfb8aa3b, v51
	v_mul_f32_e32 v56, 0xbfb8aa3b, v56
	v_mov_b32_e32 v181, v141
	v_mul_f32_e32 v52, 0xbfb8aa3b, v52
	v_mul_f32_e32 v57, 0xbfb8aa3b, v57
	v_mul_f32_e32 v53, 0xbfb8aa3b, v53
	v_rcp_f32_e32 v58, v58
	v_rcp_f32_e32 v59, v59
	v_rcp_f32_e32 v64, v64
	v_rcp_f32_e32 v60, v60
	v_rcp_f32_e32 v65, v65
	v_rcp_f32_e32 v61, v61
	v_exp_f32_e32 v54, v54
	v_exp_f32_e32 v50, v50
	v_exp_f32_e32 v55, v55
	v_exp_f32_e32 v51, v51
	v_exp_f32_e32 v56, v56
	v_add_f32_e32 v167, 1.0, v182
	v_rcp_f32_e32 v167, v167
	v_mov_b32_e32 v126, v181
	v_sub_f32_e32 v181, 1.0, v165
	v_fma_f32 v127, v127, v181, v165
	v_log_f32_e32 v186, v127
	v_mul_f32_e32 v127, 0xbfb8aa3b, v128
	v_mul_f32_e32 v128, 0xbfb8aa3b, v129
	v_exp_f32_e32 v127, v127
	v_exp_f32_e32 v128, v128
	v_sub_f32_e32 v182, 1.0, v177
	v_fma_f32 v167, v167, v182, v177
	v_add_f32_e32 v127, 1.0, v127
	v_add_f32_e32 v128, 1.0, v128
	v_rcp_f32_e32 v127, v127
	v_rcp_f32_e32 v129, v128
	v_sub_f32_e32 v128, 1.0, v176
	v_log_f32_e32 v167, v167
	v_fma_f32 v127, v127, v185, v175
	v_fma_f32 v129, v129, v128, v176
	v_log_f32_e32 v187, v127
	v_sub_f32_e32 v127, 1.0, v180
	v_log_f32_e32 v188, v129
	v_sub_f32_e32 v129, 1.0, v126
	v_fma_f32 v124, v124, v127, v180
	v_fma_f32 v125, v125, v129, v126
	v_log_f32_e32 v124, v124
	v_log_f32_e32 v125, v125
	v_cvt_f16_f32_e32 v167, v167
	v_cvt_f16_f32_sdwa v186, v186 dst_sel:WORD_1 dst_unused:UNUSED_PAD src0_sel:DWORD
	v_cvt_f16_f32_e32 v187, v187
	v_cvt_f16_f32_sdwa v188, v188 dst_sel:WORD_1 dst_unused:UNUSED_PAD src0_sel:DWORD
	v_cvt_f16_f32_e32 v124, v124
	v_cvt_f16_f32_sdwa v125, v125 dst_sel:WORD_1 dst_unused:UNUSED_PAD src0_sel:DWORD
	v_or_b32_e32 v186, v186, v167
	v_ashrrev_i32_e32 v167, 31, v166
	v_or_b32_e32 v187, v188, v187
	v_or_b32_e32 v188, v123, v122
	v_or_b32_e32 v189, v125, v124
	v_lshl_add_u64 v[124:125], s[64:65], 0, v[168:169]
	v_lshlrev_b64 v[122:123], 1, v[166:167]
	v_add_u32_e32 v166, 0x80, v166
	v_lshl_add_u64 v[124:125], v[124:125], 0, v[122:123]
	global_store_dwordx4 v[124:125], v[186:189], off
	v_fma_f32 v110, v110, v182, v177
	v_fma_f32 v111, v111, v181, v165
	v_log_f32_e32 v110, v110
	v_mov_b32_e32 v166, v142
	v_log_f32_e32 v111, v111
	v_fma_f32 v108, v108, v127, v180
	v_fma_f32 v113, v113, v128, v176
	v_fma_f32 v109, v109, v129, v126
	v_log_f32_e32 v108, v108
	v_log_f32_e32 v113, v113
	v_log_f32_e32 v109, v109
	v_cvt_f16_f32_e32 v110, v110
	v_cvt_f16_f32_sdwa v111, v111 dst_sel:WORD_1 dst_unused:UNUSED_PAD src0_sel:DWORD
	v_cvt_f16_f32_sdwa v113, v113 dst_sel:WORD_1 dst_unused:UNUSED_PAD src0_sel:DWORD
	v_cvt_f16_f32_sdwa v109, v109 dst_sel:WORD_1 dst_unused:UNUSED_PAD src0_sel:DWORD
	v_fma_f32 v94, v94, v182, v177
	v_fma_f32 v95, v95, v181, v165
	v_log_f32_e32 v94, v94
	v_mov_b32_e32 v166, v134
	v_log_f32_e32 v95, v95
	v_fma_f32 v92, v92, v127, v180
	v_fma_f32 v97, v97, v128, v176
	v_fma_f32 v93, v93, v129, v126
	v_log_f32_e32 v92, v92
	v_log_f32_e32 v97, v97
	v_log_f32_e32 v93, v93
	v_cvt_f16_f32_e32 v94, v94
	v_cvt_f16_f32_sdwa v95, v95 dst_sel:WORD_1 dst_unused:UNUSED_PAD src0_sel:DWORD
	v_cvt_f16_f32_sdwa v97, v97 dst_sel:WORD_1 dst_unused:UNUSED_PAD src0_sel:DWORD
	v_cvt_f16_f32_sdwa v93, v93 dst_sel:WORD_1 dst_unused:UNUSED_PAD src0_sel:DWORD
	v_fma_f32 v78, v78, v182, v177
	v_fma_f32 v79, v79, v181, v165
	v_log_f32_e32 v78, v78
	v_log_f32_e32 v79, v79
	v_fma_f32 v76, v76, v127, v180
	v_mov_b32_e32 v168, v142
	v_fma_f32 v81, v81, v128, v176
	v_fma_f32 v77, v77, v129, v126
	v_log_f32_e32 v76, v76
	v_log_f32_e32 v81, v81
	v_log_f32_e32 v77, v77
	v_cvt_f16_f32_e32 v78, v78
	v_cvt_f16_f32_sdwa v79, v79 dst_sel:WORD_1 dst_unused:UNUSED_PAD src0_sel:DWORD
	v_cvt_f16_f32_sdwa v81, v81 dst_sel:WORD_1 dst_unused:UNUSED_PAD src0_sel:DWORD
	v_cvt_f16_f32_sdwa v77, v77 dst_sel:WORD_1 dst_unused:UNUSED_PAD src0_sel:DWORD
	v_exp_f32_e32 v52, v52
	v_exp_f32_e32 v57, v57
	v_exp_f32_e32 v53, v53
	v_fma_f32 v62, v62, v182, v177
	v_fma_f32 v63, v63, v181, v165
	v_mul_f32_e32 v46, 0xbfb8aa3b, v46
	v_mul_f32_e32 v47, 0xbfb8aa3b, v47
	v_mov_b32_e32 v168, v135
	v_log_f32_e32 v62, v62
	v_fma_f32 v58, v58, v184, v178
	v_log_f32_e32 v63, v63
	v_fma_f32 v59, v59, v183, v179
	v_fma_f32 v64, v64, v185, v175
	v_fma_f32 v60, v60, v127, v180
	v_fma_f32 v65, v65, v128, v176
	v_fma_f32 v61, v61, v129, v126
	v_add_f32_e32 v54, 1.0, v54
	v_add_f32_e32 v50, 1.0, v50
	v_add_f32_e32 v55, 1.0, v55
	v_add_f32_e32 v51, 1.0, v51
	v_mov_b32_e32 v167, v168
	v_add_f32_e32 v56, 1.0, v56
	v_add_f32_e32 v52, 1.0, v52
	v_mov_b32_e32 v169, v142
	v_add_f32_e32 v57, 1.0, v57
	v_add_f32_e32 v53, 1.0, v53
	v_exp_f32_e32 v46, v46
	v_mul_f32_e32 v42, 0xbfb8aa3b, v42
	v_exp_f32_e32 v47, v47
	v_mul_f32_e32 v43, 0xbfb8aa3b, v43
	v_mul_f32_e32 v48, 0xbfb8aa3b, v48
	v_mul_f32_e32 v44, 0xbfb8aa3b, v44
	v_mul_f32_e32 v49, 0xbfb8aa3b, v49
	v_mul_f32_e32 v45, 0xbfb8aa3b, v45
	v_log_f32_e32 v58, v58
	v_log_f32_e32 v59, v59
	v_log_f32_e32 v64, v64
	v_log_f32_e32 v60, v60
	v_log_f32_e32 v65, v65
	v_log_f32_e32 v61, v61
	v_rcp_f32_e32 v54, v54
	v_rcp_f32_e32 v50, v50
	v_mov_b32_e32 v169, v136
	v_rcp_f32_e32 v55, v55
	v_rcp_f32_e32 v51, v51
	v_rcp_f32_e32 v56, v56
	v_rcp_f32_e32 v52, v52
	v_rcp_f32_e32 v57, v57
	v_rcp_f32_e32 v53, v53
	v_exp_f32_e32 v42, v42
	v_exp_f32_e32 v43, v43
	v_exp_f32_e32 v48, v48
	v_exp_f32_e32 v44, v44
	v_mov_b32_e32 v168, v169
	v_exp_f32_e32 v49, v49
	v_exp_f32_e32 v45, v45
	v_mov_b32_e32 v186, v142
	v_cvt_f16_f32_e32 v62, v62
	v_cvt_f16_f32_sdwa v63, v63 dst_sel:WORD_1 dst_unused:UNUSED_PAD src0_sel:DWORD
	v_add_f32_e32 v46, 1.0, v46
	v_add_f32_e32 v47, 1.0, v47
	v_cvt_f16_f32_e32 v64, v64
	v_cvt_f16_f32_sdwa v65, v65 dst_sel:WORD_1 dst_unused:UNUSED_PAD src0_sel:DWORD
	v_cvt_f16_f32_sdwa v61, v61 dst_sel:WORD_1 dst_unused:UNUSED_PAD src0_sel:DWORD
	v_rcp_f32_e32 v46, v46
	v_add_f32_e32 v42, 1.0, v42
	v_rcp_f32_e32 v47, v47
	v_add_f32_e32 v43, 1.0, v43
	v_add_f32_e32 v48, 1.0, v48
	v_add_f32_e32 v44, 1.0, v44
	v_add_f32_e32 v49, 1.0, v49
	v_add_f32_e32 v45, 1.0, v45
	v_mul_f32_e32 v38, 0xbfb8aa3b, v38
	v_mul_f32_e32 v34, 0xbfb8aa3b, v34
	v_mul_f32_e32 v39, 0xbfb8aa3b, v39
	v_mul_f32_e32 v35, 0xbfb8aa3b, v35
	v_mul_f32_e32 v40, 0xbfb8aa3b, v40
	v_mov_b32_e32 v186, v137
	v_mul_f32_e32 v36, 0xbfb8aa3b, v36
	v_mul_f32_e32 v41, 0xbfb8aa3b, v41
	v_mul_f32_e32 v37, 0xbfb8aa3b, v37
	v_rcp_f32_e32 v42, v42
	v_rcp_f32_e32 v43, v43
	v_rcp_f32_e32 v48, v48
	v_rcp_f32_e32 v44, v44
	v_rcp_f32_e32 v49, v49
	v_mov_b32_e32 v169, v186
	v_rcp_f32_e32 v45, v45
	v_exp_f32_e32 v38, v38
	v_mov_b32_e32 v187, v142
	v_exp_f32_e32 v34, v34
	v_exp_f32_e32 v39, v39
	v_exp_f32_e32 v35, v35
	v_exp_f32_e32 v40, v40
	v_exp_f32_e32 v36, v36
	v_exp_f32_e32 v41, v41
	v_exp_f32_e32 v37, v37
	v_fma_f32 v46, v46, v182, v177
	v_fma_f32 v47, v47, v181, v165
	v_mul_f32_e32 v30, 0xbfb8aa3b, v30
	v_mul_f32_e32 v26, 0xbfb8aa3b, v26
	v_mul_f32_e32 v31, 0xbfb8aa3b, v31
	v_mul_f32_e32 v10, 0xbfb8aa3b, v10
	v_log_f32_e32 v46, v46
	v_fma_f32 v42, v42, v184, v178
	v_log_f32_e32 v47, v47
	v_fma_f32 v43, v43, v183, v179
	v_fma_f32 v48, v48, v185, v175
	v_fma_f32 v44, v44, v127, v180
	v_fma_f32 v49, v49, v128, v176
	v_fma_f32 v45, v45, v129, v126
	v_add_f32_e32 v38, 1.0, v38
	v_mov_b32_e32 v187, v130
	v_add_f32_e32 v34, 1.0, v34
	v_add_f32_e32 v39, 1.0, v39
	v_add_f32_e32 v35, 1.0, v35
	v_add_f32_e32 v40, 1.0, v40
	v_add_f32_e32 v36, 1.0, v36
	v_add_f32_e32 v41, 1.0, v41
	v_mov_b32_e32 v186, v187
	v_add_f32_e32 v37, 1.0, v37
	v_exp_f32_e32 v30, v30
	v_mov_b32_e32 v188, v142
	v_exp_f32_e32 v26, v26
	v_exp_f32_e32 v31, v31
	v_mul_f32_e32 v27, 0xbfb8aa3b, v27
	v_mul_f32_e32 v32, 0xbfb8aa3b, v32
	v_mul_f32_e32 v28, 0xbfb8aa3b, v28
	v_mul_f32_e32 v33, 0xbfb8aa3b, v33
	v_mul_f32_e32 v29, 0xbfb8aa3b, v29
	v_mul_f32_e32 v18, 0xbfb8aa3b, v18
	v_exp_f32_e32 v10, v10
	v_mul_f32_e32 v2, 0xbfb8aa3b, v2
	v_log_f32_e32 v42, v42
	v_log_f32_e32 v43, v43
	v_log_f32_e32 v48, v48
	v_log_f32_e32 v44, v44
	v_log_f32_e32 v49, v49
	v_log_f32_e32 v45, v45
	v_rcp_f32_e32 v38, v38
	v_rcp_f32_e32 v34, v34
	v_rcp_f32_e32 v39, v39
	v_rcp_f32_e32 v35, v35
	v_rcp_f32_e32 v40, v40
	v_rcp_f32_e32 v36, v36
	v_rcp_f32_e32 v41, v41
	v_rcp_f32_e32 v37, v37
	v_mov_b32_e32 v188, v131
	v_exp_f32_e32 v27, v27
	v_exp_f32_e32 v32, v32
	v_exp_f32_e32 v28, v28
	v_exp_f32_e32 v33, v33
	v_mov_b32_e32 v187, v188
	v_exp_f32_e32 v29, v29
	v_mov_b32_e32 v190, v142
	v_exp_f32_e32 v18, v18
	v_exp_f32_e32 v2, v2
	v_cvt_f16_f32_e32 v46, v46
	v_cvt_f16_f32_sdwa v47, v47 dst_sel:WORD_1 dst_unused:UNUSED_PAD src0_sel:DWORD
	v_add_f32_e32 v30, 1.0, v30
	v_add_f32_e32 v26, 1.0, v26
	v_add_f32_e32 v31, 1.0, v31
	v_add_f32_e32 v10, 1.0, v10
	v_mul_f32_e32 v11, 0xbfb8aa3b, v11
	v_mul_f32_e32 v12, 0xbfb8aa3b, v12
	v_cvt_f16_f32_e32 v48, v48
	v_cvt_f16_f32_sdwa v49, v49 dst_sel:WORD_1 dst_unused:UNUSED_PAD src0_sel:DWORD
	v_cvt_f16_f32_sdwa v45, v45 dst_sel:WORD_1 dst_unused:UNUSED_PAD src0_sel:DWORD
	v_rcp_f32_e32 v30, v30
	v_rcp_f32_e32 v26, v26
	v_rcp_f32_e32 v31, v31
	v_add_f32_e32 v27, 1.0, v27
	v_add_f32_e32 v32, 1.0, v32
	v_add_f32_e32 v28, 1.0, v28
	v_add_f32_e32 v33, 1.0, v33
	v_add_f32_e32 v29, 1.0, v29
	v_mul_f32_e32 v22, 0xbfb8aa3b, v22
	v_add_f32_e32 v18, 1.0, v18
	v_mul_f32_e32 v23, 0xbfb8aa3b, v23
	v_mul_f32_e32 v19, 0xbfb8aa3b, v19
	v_mul_f32_e32 v24, 0xbfb8aa3b, v24
	v_mov_b32_e32 v190, v132
	v_mul_f32_e32 v20, 0xbfb8aa3b, v20
	v_mul_f32_e32 v25, 0xbfb8aa3b, v25
	v_mov_b32_e32 v188, v190
	v_mul_f32_e32 v21, 0xbfb8aa3b, v21
	v_rcp_f32_e32 v10, v10
	v_exp_f32_e32 v11, v11
	v_exp_f32_e32 v12, v12
	v_add_f32_e32 v2, 1.0, v2
	v_mul_f32_e32 v3, 0xbfb8aa3b, v3
	v_mul_f32_e32 v4, 0xbfb8aa3b, v4
	v_rcp_f32_e32 v27, v27
	v_mov_b32_e32 v138, v142
	v_rcp_f32_e32 v32, v32
	v_rcp_f32_e32 v28, v28
	v_rcp_f32_e32 v33, v33
	v_rcp_f32_e32 v29, v29
	v_exp_f32_e32 v22, v22
	v_rcp_f32_e32 v18, v18
	v_exp_f32_e32 v23, v23
	v_exp_f32_e32 v19, v19
	v_mov_b32_e32 v134, v138
	v_exp_f32_e32 v24, v24
	v_exp_f32_e32 v20, v20
	v_exp_f32_e32 v25, v25
	v_exp_f32_e32 v21, v21
	v_rcp_f32_e32 v2, v2
	v_exp_f32_e32 v3, v3
	v_exp_f32_e32 v4, v4
	v_fma_f32 v30, v30, v182, v177
	v_mov_b32_e32 v130, v134
	v_fma_f32 v26, v26, v184, v178
	v_fma_f32 v31, v31, v181, v165
	v_exp_f32_e32 v131, v118
	v_mul_f32_e32 v14, 0xbfb8aa3b, v14
	v_fmac_f32_e32 v178, v10, v184
	v_mul_f32_e32 v10, 0xbfb8aa3b, v15
	v_add_f32_e32 v11, 1.0, v11
	v_mov_b32_e32 v118, v133
	v_add_f32_e32 v130, 1.0, v131
	v_rcp_f32_e32 v131, v130
	v_sub_f32_e32 v130, 1.0, v166
	v_fma_f32 v102, v102, v130, v166
	v_log_f32_e32 v102, v102
	v_fma_f32 v131, v131, v130, v166
	v_log_f32_e32 v132, v131
	v_sub_f32_e32 v131, 1.0, v186
	v_fma_f32 v114, v114, v131, v186
	v_log_f32_e32 v133, v114
	v_mul_f32_e32 v114, 0xbfb8aa3b, v115
	v_exp_f32_e32 v114, v114
	v_add_f32_e32 v115, 1.0, v119
	v_rcp_f32_e32 v119, v115
	v_sub_f32_e32 v115, 1.0, v167
	v_add_f32_e32 v114, 1.0, v114
	v_rcp_f32_e32 v114, v114
	v_fma_f32 v119, v119, v115, v167
	v_log_f32_e32 v134, v119
	v_sub_f32_e32 v119, 1.0, v187
	v_fma_f32 v114, v114, v119, v187
	v_log_f32_e32 v135, v114
	v_mul_f32_e32 v114, 0xbfb8aa3b, v116
	v_exp_f32_e32 v114, v114
	v_add_f32_e32 v116, 1.0, v120
	v_rcp_f32_e32 v116, v116
	v_sub_f32_e32 v120, 1.0, v168
	v_add_f32_e32 v114, 1.0, v114
	v_rcp_f32_e32 v136, v114
	v_fma_f32 v114, v116, v120, v168
	v_log_f32_e32 v137, v114
	v_sub_f32_e32 v114, 1.0, v188
	v_fma_f32 v116, v136, v114, v188
	v_log_f32_e32 v136, v116
	v_mul_f32_e32 v116, 0xbfb8aa3b, v117
	v_exp_f32_e32 v117, v116
	v_add_f32_e32 v116, 1.0, v121
	v_rcp_f32_e32 v121, v116
	v_sub_f32_e32 v116, 1.0, v169
	v_add_f32_e32 v117, 1.0, v117
	v_rcp_f32_e32 v138, v117
	v_fma_f32 v117, v121, v116, v169
	v_log_f32_e32 v121, v117
	v_sub_f32_e32 v117, 1.0, v118
	v_fma_f32 v138, v138, v117, v118
	v_log_f32_e32 v138, v138
	v_cvt_f16_f32_e32 v132, v132
	v_cvt_f16_f32_sdwa v134, v134 dst_sel:WORD_1 dst_unused:UNUSED_PAD src0_sel:DWORD
	v_cvt_f16_f32_e32 v137, v137
	v_cvt_f16_f32_sdwa v121, v121 dst_sel:WORD_1 dst_unused:UNUSED_PAD src0_sel:DWORD
	v_cvt_f16_f32_e32 v139, v133
	v_cvt_f16_f32_sdwa v135, v135 dst_sel:WORD_1 dst_unused:UNUSED_PAD src0_sel:DWORD
	v_cvt_f16_f32_e32 v136, v136
	v_cvt_f16_f32_sdwa v138, v138 dst_sel:WORD_1 dst_unused:UNUSED_PAD src0_sel:DWORD
	v_or_b32_e32 v132, v134, v132
	v_or_b32_e32 v133, v121, v137
	v_or_b32_e32 v134, v135, v139
	v_or_b32_e32 v135, v138, v136
	global_store_dwordx4 v[124:125], v[132:135], off offset:256
	v_add_u32_e32 v124, 16, v164
	v_cvt_f16_f32_e32 v121, v106
	v_cvt_f16_f32_sdwa v132, v107 dst_sel:WORD_1 dst_unused:UNUSED_PAD src0_sel:DWORD
	v_cvt_f16_f32_e32 v133, v108
	v_fma_f32 v98, v98, v131, v186
	v_fma_f32 v103, v103, v115, v167
	v_fma_f32 v99, v99, v119, v187
	v_fma_f32 v104, v104, v120, v168
	v_fma_f32 v100, v100, v114, v188
	v_fma_f32 v105, v105, v116, v169
	v_fma_f32 v101, v101, v117, v118
	v_ashrrev_i32_e32 v125, 31, v124
	v_log_f32_e32 v98, v98
	v_log_f32_e32 v103, v103
	v_log_f32_e32 v99, v99
	v_log_f32_e32 v104, v104
	v_log_f32_e32 v100, v100
	v_log_f32_e32 v105, v105
	v_log_f32_e32 v101, v101
	v_lshlrev_b64 v[124:125], 11, v[124:125]
	v_or_b32_e32 v106, v111, v110
	v_lshl_add_u64 v[110:111], s[64:65], 0, v[124:125]
	v_or_b32_e32 v107, v113, v112
	v_or_b32_e32 v108, v132, v121
	v_or_b32_e32 v109, v109, v133
	v_lshl_add_u64 v[110:111], v[110:111], 0, v[122:123]
	global_store_dwordx4 v[110:111], v[106:109], off
	v_cvt_f16_f32_e32 v102, v102
	v_cvt_f16_f32_sdwa v103, v103 dst_sel:WORD_1 dst_unused:UNUSED_PAD src0_sel:DWORD
	v_cvt_f16_f32_e32 v104, v104
	v_cvt_f16_f32_sdwa v105, v105 dst_sel:WORD_1 dst_unused:UNUSED_PAD src0_sel:DWORD
	v_cvt_f16_f32_e32 v106, v98
	v_cvt_f16_f32_sdwa v107, v99 dst_sel:WORD_1 dst_unused:UNUSED_PAD src0_sel:DWORD
	v_cvt_f16_f32_e32 v108, v100
	v_cvt_f16_f32_sdwa v101, v101 dst_sel:WORD_1 dst_unused:UNUSED_PAD src0_sel:DWORD
	v_or_b32_e32 v98, v103, v102
	v_or_b32_e32 v99, v105, v104
	v_or_b32_e32 v100, v107, v106
	v_or_b32_e32 v101, v101, v108
	global_store_dwordx4 v[110:111], v[98:101], off offset:256
	v_cvt_f16_f32_e32 v102, v92
	v_fma_f32 v86, v86, v130, v166
	v_add_u32_e32 v98, 32, v164
	v_cvt_f16_f32_e32 v100, v90
	v_cvt_f16_f32_sdwa v101, v91 dst_sel:WORD_1 dst_unused:UNUSED_PAD src0_sel:DWORD
	v_fma_f32 v82, v82, v131, v186
	v_fma_f32 v87, v87, v115, v167
	v_fma_f32 v83, v83, v119, v187
	v_fma_f32 v88, v88, v120, v168
	v_fma_f32 v84, v84, v114, v188
	v_fma_f32 v89, v89, v116, v169
	v_fma_f32 v85, v85, v117, v118
	v_ashrrev_i32_e32 v99, 31, v98
	v_log_f32_e32 v86, v86
	v_log_f32_e32 v82, v82
	v_log_f32_e32 v87, v87
	v_log_f32_e32 v83, v83
	v_log_f32_e32 v88, v88
	v_log_f32_e32 v84, v84
	v_log_f32_e32 v89, v89
	v_log_f32_e32 v85, v85
	v_lshlrev_b64 v[98:99], 11, v[98:99]
	v_or_b32_e32 v90, v95, v94
	v_lshl_add_u64 v[94:95], s[64:65], 0, v[98:99]
	v_or_b32_e32 v91, v97, v96
	v_or_b32_e32 v92, v101, v100
	v_or_b32_e32 v93, v93, v102
	v_lshl_add_u64 v[94:95], v[94:95], 0, v[122:123]
	global_store_dwordx4 v[94:95], v[90:93], off
	v_cvt_f16_f32_e32 v86, v86
	v_cvt_f16_f32_sdwa v87, v87 dst_sel:WORD_1 dst_unused:UNUSED_PAD src0_sel:DWORD
	v_cvt_f16_f32_e32 v88, v88
	v_cvt_f16_f32_sdwa v89, v89 dst_sel:WORD_1 dst_unused:UNUSED_PAD src0_sel:DWORD
	v_cvt_f16_f32_e32 v90, v82
	v_cvt_f16_f32_sdwa v91, v83 dst_sel:WORD_1 dst_unused:UNUSED_PAD src0_sel:DWORD
	v_cvt_f16_f32_e32 v92, v84
	v_cvt_f16_f32_sdwa v85, v85 dst_sel:WORD_1 dst_unused:UNUSED_PAD src0_sel:DWORD
	v_or_b32_e32 v82, v87, v86
	v_or_b32_e32 v83, v89, v88
	v_or_b32_e32 v84, v91, v90
	v_or_b32_e32 v85, v85, v92
	global_store_dwordx4 v[94:95], v[82:85], off offset:256
	v_cvt_f16_f32_e32 v86, v76
	v_fma_f32 v70, v70, v130, v166
	v_add_u32_e32 v82, 48, v164
	v_cvt_f16_f32_e32 v84, v74
	v_cvt_f16_f32_sdwa v85, v75 dst_sel:WORD_1 dst_unused:UNUSED_PAD src0_sel:DWORD
	v_fma_f32 v66, v66, v131, v186
	v_fma_f32 v71, v71, v115, v167
	v_fma_f32 v67, v67, v119, v187
	v_fma_f32 v72, v72, v120, v168
	v_fma_f32 v68, v68, v114, v188
	v_fma_f32 v73, v73, v116, v169
	v_fma_f32 v69, v69, v117, v118
	v_ashrrev_i32_e32 v83, 31, v82
	v_log_f32_e32 v70, v70
	v_log_f32_e32 v66, v66
	v_log_f32_e32 v71, v71
	v_log_f32_e32 v67, v67
	v_log_f32_e32 v72, v72
	v_log_f32_e32 v68, v68
	v_log_f32_e32 v73, v73
	v_log_f32_e32 v69, v69
	v_lshlrev_b64 v[82:83], 11, v[82:83]
	v_or_b32_e32 v74, v79, v78
	v_lshl_add_u64 v[78:79], s[64:65], 0, v[82:83]
	v_or_b32_e32 v75, v81, v80
	v_or_b32_e32 v76, v85, v84
	v_or_b32_e32 v77, v77, v86
	v_lshl_add_u64 v[78:79], v[78:79], 0, v[122:123]
	global_store_dwordx4 v[78:79], v[74:77], off
	v_cvt_f16_f32_e32 v70, v70
	v_cvt_f16_f32_sdwa v71, v71 dst_sel:WORD_1 dst_unused:UNUSED_PAD src0_sel:DWORD
	v_cvt_f16_f32_e32 v72, v72
	v_cvt_f16_f32_sdwa v73, v73 dst_sel:WORD_1 dst_unused:UNUSED_PAD src0_sel:DWORD
	v_cvt_f16_f32_e32 v74, v66
	v_cvt_f16_f32_sdwa v75, v67 dst_sel:WORD_1 dst_unused:UNUSED_PAD src0_sel:DWORD
	v_cvt_f16_f32_e32 v76, v68
	v_cvt_f16_f32_sdwa v69, v69 dst_sel:WORD_1 dst_unused:UNUSED_PAD src0_sel:DWORD
	v_or_b32_e32 v66, v71, v70
	v_or_b32_e32 v67, v73, v72
	v_or_b32_e32 v68, v75, v74
	v_or_b32_e32 v69, v69, v76
	global_store_dwordx4 v[78:79], v[66:69], off offset:256
	v_cvt_f16_f32_e32 v70, v60
	v_fma_f32 v54, v54, v130, v166
	v_add_u32_e32 v66, 0x80, v164
	v_cvt_f16_f32_e32 v68, v58
	v_cvt_f16_f32_sdwa v69, v59 dst_sel:WORD_1 dst_unused:UNUSED_PAD src0_sel:DWORD
	v_fma_f32 v50, v50, v131, v186
	v_fma_f32 v55, v55, v115, v167
	v_fma_f32 v51, v51, v119, v187
	v_fma_f32 v56, v56, v120, v168
	v_fma_f32 v52, v52, v114, v188
	v_fma_f32 v57, v57, v116, v169
	v_fma_f32 v53, v53, v117, v118
	v_ashrrev_i32_e32 v67, 31, v66
	v_log_f32_e32 v54, v54
	v_log_f32_e32 v50, v50
	v_log_f32_e32 v55, v55
	v_log_f32_e32 v51, v51
	v_log_f32_e32 v56, v56
	v_log_f32_e32 v52, v52
	v_log_f32_e32 v57, v57
	v_log_f32_e32 v53, v53
	v_lshlrev_b64 v[66:67], 11, v[66:67]
	v_or_b32_e32 v58, v63, v62
	v_lshl_add_u64 v[62:63], s[64:65], 0, v[66:67]
	v_or_b32_e32 v59, v65, v64
	v_or_b32_e32 v60, v69, v68
	v_or_b32_e32 v61, v61, v70
	v_lshl_add_u64 v[62:63], v[62:63], 0, v[122:123]
	global_store_dwordx4 v[62:63], v[58:61], off
	v_cvt_f16_f32_e32 v54, v54
	v_cvt_f16_f32_sdwa v55, v55 dst_sel:WORD_1 dst_unused:UNUSED_PAD src0_sel:DWORD
	v_cvt_f16_f32_e32 v56, v56
	v_cvt_f16_f32_sdwa v57, v57 dst_sel:WORD_1 dst_unused:UNUSED_PAD src0_sel:DWORD
	v_cvt_f16_f32_e32 v58, v50
	v_cvt_f16_f32_sdwa v59, v51 dst_sel:WORD_1 dst_unused:UNUSED_PAD src0_sel:DWORD
	v_cvt_f16_f32_e32 v60, v52
	v_cvt_f16_f32_sdwa v53, v53 dst_sel:WORD_1 dst_unused:UNUSED_PAD src0_sel:DWORD
	v_or_b32_e32 v50, v55, v54
	v_or_b32_e32 v51, v57, v56
	v_or_b32_e32 v52, v59, v58
	v_or_b32_e32 v53, v53, v60
	global_store_dwordx4 v[62:63], v[50:53], off offset:256
	v_cvt_f16_f32_e32 v54, v44
	v_fma_f32 v38, v38, v130, v166
	v_add_u32_e32 v50, 0x90, v164
	v_cvt_f16_f32_e32 v52, v42
	v_cvt_f16_f32_sdwa v53, v43 dst_sel:WORD_1 dst_unused:UNUSED_PAD src0_sel:DWORD
	v_fma_f32 v34, v34, v131, v186
	v_fma_f32 v39, v39, v115, v167
	v_fma_f32 v35, v35, v119, v187
	v_fma_f32 v40, v40, v120, v168
	v_fma_f32 v36, v36, v114, v188
	v_fma_f32 v41, v41, v116, v169
	v_fma_f32 v37, v37, v117, v118
	v_ashrrev_i32_e32 v51, 31, v50
	v_log_f32_e32 v38, v38
	v_log_f32_e32 v34, v34
	v_log_f32_e32 v39, v39
	v_log_f32_e32 v35, v35
	v_log_f32_e32 v40, v40
	v_log_f32_e32 v36, v36
	v_log_f32_e32 v41, v41
	v_log_f32_e32 v37, v37
	v_lshlrev_b64 v[50:51], 11, v[50:51]
	v_or_b32_e32 v42, v47, v46
	v_lshl_add_u64 v[46:47], s[64:65], 0, v[50:51]
	v_or_b32_e32 v43, v49, v48
	v_or_b32_e32 v44, v53, v52
	v_or_b32_e32 v45, v45, v54
	v_lshl_add_u64 v[46:47], v[46:47], 0, v[122:123]
	v_mul_f32_e32 v16, 0xbfb8aa3b, v16
	v_add_f32_e32 v12, 1.0, v12
	v_mul_f32_e32 v17, 0xbfb8aa3b, v17
	global_store_dwordx4 v[46:47], v[42:45], off
	v_cvt_f16_f32_e32 v38, v38
	v_cvt_f16_f32_sdwa v39, v39 dst_sel:WORD_1 dst_unused:UNUSED_PAD src0_sel:DWORD
	v_cvt_f16_f32_e32 v40, v40
	v_cvt_f16_f32_sdwa v41, v41 dst_sel:WORD_1 dst_unused:UNUSED_PAD src0_sel:DWORD
	v_cvt_f16_f32_e32 v42, v34
	v_cvt_f16_f32_sdwa v43, v35 dst_sel:WORD_1 dst_unused:UNUSED_PAD src0_sel:DWORD
	v_cvt_f16_f32_e32 v44, v36
	v_cvt_f16_f32_sdwa v37, v37 dst_sel:WORD_1 dst_unused:UNUSED_PAD src0_sel:DWORD
	v_log_f32_e32 v30, v30
	v_log_f32_e32 v31, v31
	v_fma_f32 v27, v27, v183, v179
	v_fma_f32 v32, v32, v185, v175
	v_fma_f32 v28, v28, v127, v180
	v_fma_f32 v33, v33, v128, v176
	v_fma_f32 v29, v29, v129, v126
	v_add_f32_e32 v22, 1.0, v22
	v_fma_f32 v18, v18, v131, v186
	v_add_f32_e32 v23, 1.0, v23
	v_add_f32_e32 v19, 1.0, v19
	v_add_f32_e32 v24, 1.0, v24
	v_add_f32_e32 v20, 1.0, v20
	v_add_f32_e32 v25, 1.0, v25
	v_add_f32_e32 v21, 1.0, v21
	v_exp_f32_e32 v14, v14
	v_exp_f32_e32 v10, v10
	v_rcp_f32_e32 v11, v11
	v_exp_f32_e32 v16, v16
	v_rcp_f32_e32 v12, v12
	v_exp_f32_e32 v17, v17
	v_mul_f32_e32 v13, 0xbfb8aa3b, v13
	v_mul_f32_e32 v6, 0xbfb8aa3b, v6
	v_fmac_f32_e32 v186, v2, v131
	v_mul_f32_e32 v2, 0xbfb8aa3b, v7
	v_add_f32_e32 v3, 1.0, v3
	v_mul_f32_e32 v8, 0xbfb8aa3b, v8
	v_add_f32_e32 v4, 1.0, v4
	v_mul_f32_e32 v9, 0xbfb8aa3b, v9
	v_mul_f32_e32 v5, 0xbfb8aa3b, v5
	v_log_f32_e32 v26, v26
	v_log_f32_e32 v27, v27
	v_log_f32_e32 v32, v32
	v_log_f32_e32 v28, v28
	v_log_f32_e32 v33, v33
	v_log_f32_e32 v29, v29
	v_rcp_f32_e32 v22, v22
	v_rcp_f32_e32 v23, v23
	v_rcp_f32_e32 v19, v19
	v_rcp_f32_e32 v24, v24
	v_rcp_f32_e32 v20, v20
	v_rcp_f32_e32 v25, v25
	v_rcp_f32_e32 v21, v21
	v_exp_f32_e32 v13, v13
	v_exp_f32_e32 v6, v6
	v_exp_f32_e32 v2, v2
	v_rcp_f32_e32 v3, v3
	v_exp_f32_e32 v8, v8
	v_rcp_f32_e32 v4, v4
	v_exp_f32_e32 v9, v9
	v_exp_f32_e32 v5, v5
	v_or_b32_e32 v34, v39, v38
	v_or_b32_e32 v35, v41, v40
	v_or_b32_e32 v36, v43, v42
	v_or_b32_e32 v37, v37, v44
	v_cvt_f16_f32_e32 v30, v30
	v_cvt_f16_f32_sdwa v31, v31 dst_sel:WORD_1 dst_unused:UNUSED_PAD src0_sel:DWORD
	v_add_f32_e32 v14, 1.0, v14
	v_add_f32_e32 v10, 1.0, v10
	v_fmac_f32_e32 v179, v11, v183
	v_add_f32_e32 v11, 1.0, v16
	v_fmac_f32_e32 v180, v12, v127
	v_add_f32_e32 v12, 1.0, v17
	global_store_dwordx4 v[46:47], v[34:37], off offset:256
	v_cvt_f16_f32_e32 v32, v32
	v_cvt_f16_f32_sdwa v33, v33 dst_sel:WORD_1 dst_unused:UNUSED_PAD src0_sel:DWORD
	v_add_u32_e32 v34, 0xa0, v164
	v_cvt_f16_f32_e32 v36, v26
	v_cvt_f16_f32_sdwa v37, v27 dst_sel:WORD_1 dst_unused:UNUSED_PAD src0_sel:DWORD
	v_cvt_f16_f32_e32 v38, v28
	v_cvt_f16_f32_sdwa v29, v29 dst_sel:WORD_1 dst_unused:UNUSED_PAD src0_sel:DWORD
	v_fma_f32 v22, v22, v130, v166
	v_fma_f32 v23, v23, v115, v167
	v_fma_f32 v19, v19, v119, v187
	v_fma_f32 v24, v24, v120, v168
	v_fma_f32 v20, v20, v114, v188
	v_fma_f32 v25, v25, v116, v169
	v_fma_f32 v21, v21, v117, v118
	v_rcp_f32_e32 v14, v14
	v_rcp_f32_e32 v10, v10
	v_rcp_f32_e32 v11, v11
	v_rcp_f32_e32 v12, v12
	v_add_f32_e32 v13, 1.0, v13
	v_add_f32_e32 v6, 1.0, v6
	v_add_f32_e32 v2, 1.0, v2
	v_fmac_f32_e32 v187, v3, v119
	v_add_f32_e32 v3, 1.0, v8
	v_fmac_f32_e32 v188, v4, v114
	v_add_f32_e32 v4, 1.0, v9
	v_add_f32_e32 v5, 1.0, v5
	v_ashrrev_i32_e32 v35, 31, v34
	v_log_f32_e32 v22, v22
	v_log_f32_e32 v18, v18
	v_log_f32_e32 v23, v23
	v_log_f32_e32 v19, v19
	v_log_f32_e32 v24, v24
	v_log_f32_e32 v20, v20
	v_log_f32_e32 v25, v25
	v_log_f32_e32 v21, v21
	v_rcp_f32_e32 v13, v13
	v_rcp_f32_e32 v6, v6
	v_rcp_f32_e32 v2, v2
	v_rcp_f32_e32 v3, v3
	v_rcp_f32_e32 v4, v4
	v_rcp_f32_e32 v5, v5
	v_lshlrev_b64 v[34:35], 11, v[34:35]
	v_or_b32_e32 v26, v31, v30
	v_lshl_add_u64 v[30:31], s[64:65], 0, v[34:35]
	v_or_b32_e32 v27, v33, v32
	v_or_b32_e32 v28, v37, v36
	v_or_b32_e32 v29, v29, v38
	v_lshl_add_u64 v[30:31], v[30:31], 0, v[122:123]
	v_fmac_f32_e32 v177, v14, v182
	v_fmac_f32_e32 v165, v10, v181
	v_fmac_f32_e32 v175, v11, v185
	v_fmac_f32_e32 v176, v12, v128
	global_store_dwordx4 v[30:31], v[26:29], off
	v_cvt_f16_f32_e32 v22, v22
	v_cvt_f16_f32_sdwa v23, v23 dst_sel:WORD_1 dst_unused:UNUSED_PAD src0_sel:DWORD
	v_cvt_f16_f32_e32 v24, v24
	v_cvt_f16_f32_sdwa v25, v25 dst_sel:WORD_1 dst_unused:UNUSED_PAD src0_sel:DWORD
	v_cvt_f16_f32_e32 v26, v18
	v_cvt_f16_f32_sdwa v27, v19 dst_sel:WORD_1 dst_unused:UNUSED_PAD src0_sel:DWORD
	v_cvt_f16_f32_e32 v28, v20
	v_cvt_f16_f32_sdwa v21, v21 dst_sel:WORD_1 dst_unused:UNUSED_PAD src0_sel:DWORD
	v_log_f32_e32 v14, v177
	v_log_f32_e32 v15, v178
	v_log_f32_e32 v10, v165
	v_log_f32_e32 v16, v179
	v_log_f32_e32 v11, v175
	v_log_f32_e32 v12, v176
	v_fmac_f32_e32 v126, v13, v129
	v_fmac_f32_e32 v166, v6, v130
	v_fmac_f32_e32 v167, v2, v115
	v_fmac_f32_e32 v168, v3, v120
	v_fmac_f32_e32 v169, v4, v116
	v_fmac_f32_e32 v118, v5, v117
	v_log_f32_e32 v17, v180
	v_log_f32_e32 v13, v126
	v_log_f32_e32 v6, v166
	v_log_f32_e32 v7, v186
	v_log_f32_e32 v2, v167
	v_log_f32_e32 v8, v187
	v_log_f32_e32 v3, v168
	v_log_f32_e32 v9, v188
	v_log_f32_e32 v4, v169
	v_log_f32_e32 v5, v118
	v_or_b32_e32 v18, v23, v22
	v_or_b32_e32 v19, v25, v24
	v_or_b32_e32 v20, v27, v26
	v_or_b32_e32 v21, v21, v28
	v_cvt_f16_f32_e32 v14, v14
	v_cvt_f16_f32_sdwa v10, v10 dst_sel:WORD_1 dst_unused:UNUSED_PAD src0_sel:DWORD
	v_cvt_f16_f32_e32 v11, v11
	v_cvt_f16_f32_sdwa v12, v12 dst_sel:WORD_1 dst_unused:UNUSED_PAD src0_sel:DWORD
	v_cvt_f16_f32_e32 v15, v15
	v_cvt_f16_f32_sdwa v16, v16 dst_sel:WORD_1 dst_unused:UNUSED_PAD src0_sel:DWORD
	global_store_dwordx4 v[30:31], v[18:21], off offset:256
	v_cvt_f16_f32_e32 v17, v17
	v_cvt_f16_f32_sdwa v13, v13 dst_sel:WORD_1 dst_unused:UNUSED_PAD src0_sel:DWORD
	v_add_u32_e32 v18, 0xb0, v164
	v_cvt_f16_f32_e32 v6, v6
	v_cvt_f16_f32_sdwa v2, v2 dst_sel:WORD_1 dst_unused:UNUSED_PAD src0_sel:DWORD
	v_cvt_f16_f32_e32 v3, v3
	v_cvt_f16_f32_sdwa v4, v4 dst_sel:WORD_1 dst_unused:UNUSED_PAD src0_sel:DWORD
	v_cvt_f16_f32_e32 v7, v7
	v_cvt_f16_f32_sdwa v8, v8 dst_sel:WORD_1 dst_unused:UNUSED_PAD src0_sel:DWORD
	v_cvt_f16_f32_e32 v9, v9
	v_cvt_f16_f32_sdwa v5, v5 dst_sel:WORD_1 dst_unused:UNUSED_PAD src0_sel:DWORD
	v_ashrrev_i32_e32 v19, 31, v18
	v_lshlrev_b64 v[18:19], 11, v[18:19]
	v_or_b32_e32 v10, v10, v14
	v_or_b32_e32 v11, v12, v11
	v_or_b32_e32 v12, v16, v15
	v_lshl_add_u64 v[14:15], s[64:65], 0, v[18:19]
	v_or_b32_e32 v13, v13, v17
	v_lshl_add_u64 v[14:15], v[14:15], 0, v[122:123]
	v_or_b32_e32 v2, v2, v6
	v_or_b32_e32 v3, v4, v3
	v_or_b32_e32 v4, v8, v7
	v_or_b32_e32 v5, v5, v9
	global_store_dwordx4 v[14:15], v[10:13], off
	global_store_dwordx4 v[14:15], v[2:5], off offset:256
	s_andn2_b64 vcc, exec, s[4:5]
	s_mov_b64 s[4:5], -1
	s_cbranch_vccnz .LBB0_1009

.LBB0_1178:
	s_and_b64 s[14:15], s[4:5], exec
	s_cselect_b32 s98, 0, 1
	s_sub_u32 s98, s29, s98
	s_cmp_gt_u32 s98, 15
	s_cbranch_scc1 .LBB0_1177
	s_lshr_b32 s30, s98, 1
	s_bitcmp0_b32 s98, 0
	s_mov_b64 s[14:15], -1
	s_cbranch_scc1 .LBB0_1184
	ds_read_b128 v[68:71], v185 offset:17152
	ds_read_b128 v[72:75], v185
	ds_read_b128 v[84:87], v185 offset:17184
	ds_read_b128 v[88:91], v185 offset:32
	s_sub_i32 s31, 7, s30
	s_and_b64 s[14:15], s[4:5], exec
	s_waitcnt lgkmcnt(2)
	v_mfma_f32_32x32x16_bf16 v[68:83], v[68:71], v[72:75], 0
	s_cselect_b32 s14, s30, s31
	s_cmp_gt_u32 s98, 7
	s_mov_b64 s[42:43], -1
	s_waitcnt lgkmcnt(0)
	v_mfma_f32_32x32x16_bf16 v[68:83], v[84:87], v[88:91], v[68:83]
	ds_read_b128 v[84:87], v185 offset:17216
	ds_read_b128 v[88:91], v185 offset:64
	ds_read_b128 v[92:95], v185 offset:17248
	ds_read_b128 v[96:99], v185 offset:96
	s_waitcnt lgkmcnt(2)
	v_mfma_f32_32x32x16_bf16 v[68:83], v[84:87], v[88:91], v[68:83]
	s_waitcnt lgkmcnt(0)
	v_mfma_f32_32x32x16_bf16 v[68:83], v[92:95], v[96:99], v[68:83]
	ds_read_b128 v[84:87], v185 offset:17280
	ds_read_b128 v[88:91], v185 offset:128
	ds_read_b128 v[92:95], v185 offset:17312
	ds_read_b128 v[96:99], v185 offset:160
	s_waitcnt lgkmcnt(2)
	v_mfma_f32_32x32x16_bf16 v[68:83], v[84:87], v[88:91], v[68:83]
	s_waitcnt lgkmcnt(0)
	v_mfma_f32_32x32x16_bf16 v[68:83], v[92:95], v[96:99], v[68:83]
	ds_read_b128 v[84:87], v185 offset:17344
	ds_read_b128 v[88:91], v185 offset:192
	ds_read_b128 v[92:95], v185 offset:17376
	ds_read_b128 v[96:99], v185 offset:224
	s_waitcnt lgkmcnt(2)
	v_mfma_f32_32x32x16_bf16 v[68:83], v[84:87], v[88:91], v[68:83]
	ds_read_b64_tr_b16 v[84:85], v186 offset:36096
	ds_read_b64_tr_b16 v[86:87], v186 offset:38656
	ds_read_b64_tr_b16 v[88:89], v186 offset:41216
	ds_read_b64_tr_b16 v[90:91], v186 offset:43776
	s_waitcnt lgkmcnt(4)
	v_mfma_f32_32x32x16_bf16 v[68:83], v[92:95], v[96:99], v[68:83]
	v_add_u32_e32 v96, 0x2000, v187
	s_nop 10
	v_cvt_pk_bf16_f32 v68, v68, v69
	v_cvt_pk_bf16_f32 v69, v70, v71
	v_cvt_pk_bf16_f32 v70, v72, v73
	v_cvt_pk_bf16_f32 v71, v74, v75
	v_and_b32_e32 v68, v149, v68
	v_and_b32_e32 v69, v151, v69
	v_and_b32_e32 v70, v153, v70
	v_and_b32_e32 v71, v155, v71
	v_cvt_pk_bf16_f32 v72, v76, v77
	v_cvt_pk_bf16_f32 v93, v78, v79
	v_cvt_pk_bf16_f32 v94, v80, v81
	v_cvt_pk_bf16_f32 v95, v82, v83
	v_and_b32_e32 v92, v157, v72
	s_waitcnt lgkmcnt(2)
	v_mfma_f32_32x32x16_bf16 v[68:83], v[68:71], v[84:87], 0
	v_and_b32_e32 v93, v159, v93
	v_and_b32_e32 v94, v161, v94
	v_and_b32_e32 v95, v163, v95
	ds_read2_b64 v[84:87], v96 offset0:64 offset1:66
	s_waitcnt lgkmcnt(1)
	v_mfma_f32_32x32x16_bf16 v[68:83], v[92:95], v[88:91], v[68:83]
	v_cvt_pk_bf16_f32 v88, v4, v5
	v_cvt_pk_bf16_f32 v89, v6, v7
	v_cvt_pk_bf16_f32 v90, v8, v9
	v_cvt_pk_bf16_f32 v91, v10, v11
	s_waitcnt lgkmcnt(0)
	s_nop 0
	v_mfma_f32_32x32x16_bf16 v[68:83], v[84:87], v[88:91], v[68:83]
	ds_read2_b64 v[84:87], v96 offset0:68 offset1:70
	v_cvt_pk_bf16_f32 v88, v12, v13
	v_cvt_pk_bf16_f32 v89, v14, v15
	v_cvt_pk_bf16_f32 v90, v16, v17
	v_cvt_pk_bf16_f32 v91, v18, v19
	s_waitcnt lgkmcnt(0)
	s_nop 0
	v_mfma_f32_32x32x16_bf16 v[68:83], v[84:87], v[88:91], v[68:83]
	ds_read2_b64 v[84:87], v96 offset0:72 offset1:74
	v_cvt_pk_bf16_f32 v88, v52, v53
	v_cvt_pk_bf16_f32 v89, v54, v55
	v_cvt_pk_bf16_f32 v90, v56, v57
	v_cvt_pk_bf16_f32 v91, v58, v59
	s_waitcnt lgkmcnt(0)
	s_nop 0
	v_mfma_f32_32x32x16_bf16 v[68:83], v[84:87], v[88:91], v[68:83]
	ds_read2_b64 v[84:87], v96 offset0:76 offset1:78
	v_cvt_pk_bf16_f32 v88, v60, v61
	v_cvt_pk_bf16_f32 v89, v62, v63
	v_cvt_pk_bf16_f32 v90, v64, v65
	v_cvt_pk_bf16_f32 v91, v66, v67
	s_waitcnt lgkmcnt(0)
	s_nop 0
	v_mfma_f32_32x32x16_bf16 v[68:83], v[84:87], v[88:91], v[68:83]
	ds_read2_b64 v[84:87], v96 offset0:80 offset1:82
	v_cvt_pk_bf16_f32 v88, v36, v37
	v_cvt_pk_bf16_f32 v89, v38, v39
	v_cvt_pk_bf16_f32 v90, v40, v41
	v_cvt_pk_bf16_f32 v91, v42, v43
	s_waitcnt lgkmcnt(0)
	s_nop 0
	v_mfma_f32_32x32x16_bf16 v[68:83], v[84:87], v[88:91], v[68:83]
	ds_read2_b64 v[84:87], v96 offset0:84 offset1:86
	v_cvt_pk_bf16_f32 v88, v44, v45
	v_cvt_pk_bf16_f32 v89, v46, v47
	v_cvt_pk_bf16_f32 v90, v48, v49
	v_cvt_pk_bf16_f32 v91, v50, v51
	s_waitcnt lgkmcnt(0)
	s_nop 0
	v_mfma_f32_32x32x16_bf16 v[68:83], v[84:87], v[88:91], v[68:83]
	ds_read2_b64 v[84:87], v96 offset0:88 offset1:90
	v_cvt_pk_bf16_f32 v88, v20, v21
	v_cvt_pk_bf16_f32 v89, v22, v23
	v_cvt_pk_bf16_f32 v90, v24, v25
	v_cvt_pk_bf16_f32 v91, v26, v27
	s_waitcnt lgkmcnt(0)
	s_nop 0
	v_mfma_f32_32x32x16_bf16 v[68:83], v[84:87], v[88:91], v[68:83]
	ds_read2_b64 v[84:87], v96 offset0:92 offset1:94
	v_cvt_pk_bf16_f32 v88, v28, v29
	v_cvt_pk_bf16_f32 v89, v30, v31
	v_cvt_pk_bf16_f32 v90, v32, v33
	v_cvt_pk_bf16_f32 v91, v34, v35
	s_waitcnt lgkmcnt(0)
	s_nop 0
	v_mfma_f32_32x32x16_bf16 v[68:83], v[84:87], v[88:91], v[68:83]
	s_cbranch_scc1 .LBB0_1181
	s_mov_b64 s[42:43], 0
